# P3 chunk-carry phase hand-written: 8 waves x 16-chunk segments per workgroup, composites through LDS (one load latency instead of four)
# speedup vs baseline: 1.0065x; 1.0029x over previous
; DI void phase_carry(const Params& p) {
;     const int tid = threadIdx.x;
;     if (tid >= 64) return;
;     const f32x2* AGG = (const f32x2*)(p.ws + WS_AGG); float* CAR = (float*)(p.ws + WS_CAR);
;     for (int w = blockIdx.x; w < 64; w += gridDim.x) {
;         const int id = w * 64 + tid, d = id >> 11, ch = id & 2047;
;         const f32x2* ag = AGG + (size_t)d * 128 * 2048 + ch; float* car = CAR + (size_t)d * 128 * 2048 + ch;
;         float cin = 0.f;
;         for (int b = 0; b < 4; ++b) {
;             f32x2 v[32];
; #pragma unroll
;             for (int u = 0; u < 32; ++u) { const int k = b * 32 + u, cc = d == 0 ? k : 127 - k; v[u] = ag[(size_t)cc * 2048]; }
; #pragma unroll
;             for (int u = 0; u < 32; ++u) { const int k = b * 32 + u, cc = d == 0 ? k : 127 - k; car[(size_t)cc * 2048] = cin; cin = fmaf(v[u][0], cin, v[u][1]); }
;         }
;     }
; }
.LBB0_316:
	s_waitcnt lgkmcnt(0)
	s_cmp_lt_i32 s8, 4
	s_cselect_b64 s[4:5], -1, 0
	s_cmp_gt_i32 s9, 3
	s_cselect_b64 s[6:7], -1, 0
	s_and_b64 s[6:7], s[4:5], s[6:7]
	v_cmp_gt_u32_e32 vcc, 64, v202
	s_mov_b64 s[10:11], s[6:7]
	s_waitcnt vmcnt(0)
	v_mov_b32_e32 v1, s9
	s_and_saveexec_b64 s[6:7], s[10:11]
	s_cbranch_execz .LBB0_324
	s_cmp_gt_i32 s2, 63
	s_cbranch_scc1 .LBB0_323
	s_load_dwordx2 s[10:11], s[0:1], 0x80
	v_and_b32_e32 v0, 63, v202
	v_lshrrev_b32_e32 v4, 6, v202
	s_lshr_b32 s12, s2, 5
	s_and_b32 s13, s2, 31
	s_lshl_b32 s13, s13, 6
	s_nop 1
	v_readfirstlane_b32 s14, v4
	v_add_u32_e32 v0, s13, v0
	s_nop 3
	s_lshl_b32 s15, s14, 4
	s_sub_i32 s16, 0x7f, s15
	s_mov_b32 s17, 0x4000
	s_mov_b32 s18, 0xffffc000
	s_mov_b32 s19, 0x2000
	s_mov_b32 s86, 0xffffe000
	s_cmp_eq_u32 s12, 0
	s_cselect_b32 s15, s15, s16
	s_cselect_b32 s17, s17, s18
	s_cselect_b32 s18, s19, s86
	s_lshl_b32 s19, s12, 7
	s_add_i32 s15, s15, s19
	s_lshl_b32 s19, s15, 14
	s_lshl_b32 s15, s15, 13
	v_lshl_add_u32 v2, v0, 3, s19
	v_lshl_add_u32 v3, v0, 2, s15
	s_waitcnt lgkmcnt(0)
	s_add_u32 s82, s10, 0x1ba00000
	s_addc_u32 s83, s11, 0
	s_add_u32 s84, s10, 0x1c200000
	s_addc_u32 s85, s11, 0
	global_load_dwordx2 v[10:11], v2, s[82:83]
	v_add_u32_e32 v2, s17, v2
	global_load_dwordx2 v[12:13], v2, s[82:83]
	v_add_u32_e32 v2, s17, v2
	global_load_dwordx2 v[14:15], v2, s[82:83]
	v_add_u32_e32 v2, s17, v2
	global_load_dwordx2 v[16:17], v2, s[82:83]
	v_add_u32_e32 v2, s17, v2
	global_load_dwordx2 v[18:19], v2, s[82:83]
	v_add_u32_e32 v2, s17, v2
	global_load_dwordx2 v[20:21], v2, s[82:83]
	v_add_u32_e32 v2, s17, v2
	global_load_dwordx2 v[22:23], v2, s[82:83]
	v_add_u32_e32 v2, s17, v2
	global_load_dwordx2 v[24:25], v2, s[82:83]
	v_add_u32_e32 v2, s17, v2
	global_load_dwordx2 v[26:27], v2, s[82:83]
	v_add_u32_e32 v2, s17, v2
	global_load_dwordx2 v[28:29], v2, s[82:83]
	v_add_u32_e32 v2, s17, v2
	global_load_dwordx2 v[30:31], v2, s[82:83]
	v_add_u32_e32 v2, s17, v2
	global_load_dwordx2 v[32:33], v2, s[82:83]
	v_add_u32_e32 v2, s17, v2
	global_load_dwordx2 v[34:35], v2, s[82:83]
	v_add_u32_e32 v2, s17, v2
	global_load_dwordx2 v[36:37], v2, s[82:83]
	v_add_u32_e32 v2, s17, v2
	global_load_dwordx2 v[38:39], v2, s[82:83]
	v_add_u32_e32 v2, s17, v2
	global_load_dwordx2 v[40:41], v2, s[82:83]
	v_mov_b32_e32 v6, 1.0
	v_mov_b32_e32 v7, 0
	s_waitcnt vmcnt(15)
	v_fma_f32 v7, v10, v7, v11
	v_mul_f32_e32 v6, v6, v10
	s_waitcnt vmcnt(14)
	v_fma_f32 v7, v12, v7, v13
	v_mul_f32_e32 v6, v6, v12
	s_waitcnt vmcnt(13)
	v_fma_f32 v7, v14, v7, v15
	v_mul_f32_e32 v6, v6, v14
	s_waitcnt vmcnt(12)
	v_fma_f32 v7, v16, v7, v17
	v_mul_f32_e32 v6, v6, v16
	s_waitcnt vmcnt(11)
	v_fma_f32 v7, v18, v7, v19
	v_mul_f32_e32 v6, v6, v18
	s_waitcnt vmcnt(10)
	v_fma_f32 v7, v20, v7, v21
	v_mul_f32_e32 v6, v6, v20
	s_waitcnt vmcnt(9)
	v_fma_f32 v7, v22, v7, v23
	v_mul_f32_e32 v6, v6, v22
	s_waitcnt vmcnt(8)
	v_fma_f32 v7, v24, v7, v25
	v_mul_f32_e32 v6, v6, v24
	s_waitcnt vmcnt(7)
	v_fma_f32 v7, v26, v7, v27
	v_mul_f32_e32 v6, v6, v26
	s_waitcnt vmcnt(6)
	v_fma_f32 v7, v28, v7, v29
	v_mul_f32_e32 v6, v6, v28
	s_waitcnt vmcnt(5)
	v_fma_f32 v7, v30, v7, v31
	v_mul_f32_e32 v6, v6, v30
	s_waitcnt vmcnt(4)
	v_fma_f32 v7, v32, v7, v33
	v_mul_f32_e32 v6, v6, v32
	s_waitcnt vmcnt(3)
	v_fma_f32 v7, v34, v7, v35
	v_mul_f32_e32 v6, v6, v34
	s_waitcnt vmcnt(2)
	v_fma_f32 v7, v36, v7, v37
	v_mul_f32_e32 v6, v6, v36
	s_waitcnt vmcnt(1)
	v_fma_f32 v7, v38, v7, v39
	v_mul_f32_e32 v6, v6, v38
	s_waitcnt vmcnt(0)
	v_fma_f32 v7, v40, v7, v41
	v_mul_f32_e32 v6, v6, v40
	v_lshlrev_b32_e32 v5, 3, v202
	ds_write_b64 v5, v[6:7]
	s_waitcnt lgkmcnt(0)
	s_barrier
	v_and_b32_e32 v8, 63, v202
	v_lshlrev_b32_e32 v8, 3, v8
	ds_read_b64 v[50:51], v8
	ds_read_b64 v[52:53], v8 offset:512
	ds_read_b64 v[54:55], v8 offset:1024
	ds_read_b64 v[56:57], v8 offset:1536
	ds_read_b64 v[58:59], v8 offset:2048
	ds_read_b64 v[60:61], v8 offset:2560
	ds_read_b64 v[62:63], v8 offset:3072
	v_mov_b32_e32 v9, 0
	s_waitcnt lgkmcnt(0)
	s_cmp_gt_u32 s14, 0
	s_cbranch_scc0 .Lp3_c0_done
	v_fma_f32 v9, v50, v9, v51
	s_cmp_gt_u32 s14, 1
	s_cbranch_scc0 .Lp3_c0_done
	v_fma_f32 v9, v52, v9, v53
	s_cmp_gt_u32 s14, 2
	s_cbranch_scc0 .Lp3_c0_done
	v_fma_f32 v9, v54, v9, v55
	s_cmp_gt_u32 s14, 3
	s_cbranch_scc0 .Lp3_c0_done
	v_fma_f32 v9, v56, v9, v57
	s_cmp_gt_u32 s14, 4
	s_cbranch_scc0 .Lp3_c0_done
	v_fma_f32 v9, v58, v9, v59
	s_cmp_gt_u32 s14, 5
	s_cbranch_scc0 .Lp3_c0_done
	v_fma_f32 v9, v60, v9, v61
	s_cmp_gt_u32 s14, 6
	s_cbranch_scc0 .Lp3_c0_done
	v_fma_f32 v9, v62, v9, v63
.Lp3_c0_done:
	global_store_dword v3, v9, s[84:85]
	v_fma_f32 v9, v10, v9, v11
	v_add_u32_e32 v3, s18, v3
	global_store_dword v3, v9, s[84:85]
	v_fma_f32 v9, v12, v9, v13
	v_add_u32_e32 v3, s18, v3
	global_store_dword v3, v9, s[84:85]
	v_fma_f32 v9, v14, v9, v15
	v_add_u32_e32 v3, s18, v3
	global_store_dword v3, v9, s[84:85]
	v_fma_f32 v9, v16, v9, v17
	v_add_u32_e32 v3, s18, v3
	global_store_dword v3, v9, s[84:85]
	v_fma_f32 v9, v18, v9, v19
	v_add_u32_e32 v3, s18, v3
	global_store_dword v3, v9, s[84:85]
	v_fma_f32 v9, v20, v9, v21
	v_add_u32_e32 v3, s18, v3
	global_store_dword v3, v9, s[84:85]
	v_fma_f32 v9, v22, v9, v23
	v_add_u32_e32 v3, s18, v3
	global_store_dword v3, v9, s[84:85]
	v_fma_f32 v9, v24, v9, v25
	v_add_u32_e32 v3, s18, v3
	global_store_dword v3, v9, s[84:85]
	v_fma_f32 v9, v26, v9, v27
	v_add_u32_e32 v3, s18, v3
	global_store_dword v3, v9, s[84:85]
	v_fma_f32 v9, v28, v9, v29
	v_add_u32_e32 v3, s18, v3
	global_store_dword v3, v9, s[84:85]
	v_fma_f32 v9, v30, v9, v31
	v_add_u32_e32 v3, s18, v3
	global_store_dword v3, v9, s[84:85]
	v_fma_f32 v9, v32, v9, v33
	v_add_u32_e32 v3, s18, v3
	global_store_dword v3, v9, s[84:85]
	v_fma_f32 v9, v34, v9, v35
	v_add_u32_e32 v3, s18, v3
	global_store_dword v3, v9, s[84:85]
	v_fma_f32 v9, v36, v9, v37
	v_add_u32_e32 v3, s18, v3
	global_store_dword v3, v9, s[84:85]
	v_fma_f32 v9, v38, v9, v39
	v_add_u32_e32 v3, s18, v3
	global_store_dword v3, v9, s[84:85]
	v_fma_f32 v9, v40, v9, v41
	s_load_dword s9, s[0:1], 0xcc
